# MLP-in GEMM K-loop: 4 of 6 LDS-DMA loads of each SP2 load segment moved into the following MFMA block, vmcnt recounted
# baseline (speedup 1.0000x reference)
.LBB0_101:
	s_add_u32 s16, s14, 0xfff80080
	s_addc_u32 s17, s15, -1
	s_add_i32 s49, 0, 0x10000
	s_cmp_eq_u32 s48, 28
	s_cselect_b32 s19, s11, s17
	s_cselect_b32 s18, s44, s16
	v_add_u32_e32 v144, s49, v147
	s_cselect_b32 s17, s9, s47
	s_cselect_b32 s16, s45, s46
	s_add_i32 s52, 0, 0x14000
	ds_read_b128 v[140:143], v144
	ds_read_b128 v[150:153], v144 offset:1024
	ds_read_b128 v[154:157], v144 offset:2048
	ds_read_b128 v[158:161], v144 offset:3072
	v_add_u32_e32 v144, s52, v147
	ds_read_b128 v[162:165], v144
	ds_read_b128 v[166:169], v144 offset:1024
	ds_read_b128 v[170:173], v144 offset:2048
	ds_read_b128 v[174:177], v144 offset:3072
	v_lshl_add_u64 v[144:145], s[14:15], 0, v[138:139]
	s_add_i32 m0, s23, 0xc000
	ds_read_b128 v[178:181], v149
	ds_read_b128 v[182:185], v149 offset:1024
	ds_read_b128 v[186:189], v149 offset:2048
	ds_read_b128 v[190:193], v149 offset:3072
	ds_read_b128 v[194:197], v149 offset:4096
	ds_read_b128 v[198:201], v149 offset:5120
	ds_read_b128 v[202:205], v149 offset:6144
	ds_read_b128 v[206:209], v149 offset:7168
	global_load_lds_dwordx4 v[144:145], off
	v_lshl_add_u64 v[144:145], s[14:15], 0, v[136:137]
	s_add_i32 m0, s23, 0xe000
	s_nop 0
	global_load_lds_dwordx4 v[144:145], off
	s_waitcnt vmcnt(8)
	s_waitcnt lgkmcnt(0)
	s_barrier
	s_setprio 1
	s_waitcnt lgkmcnt(0)
	v_mfma_f32_16x16x32_bf16 v[124:127], v[140:143], v[178:181], v[124:127]
	v_mfma_f32_16x16x32_bf16 v[120:123], v[154:157], v[178:181], v[120:123]
	v_mfma_f32_16x16x32_bf16 v[108:111], v[140:143], v[186:189], v[108:111]
	v_mfma_f32_16x16x32_bf16 v[104:107], v[154:157], v[186:189], v[104:107]
	v_mfma_f32_16x16x32_bf16 v[92:95], v[140:143], v[194:197], v[92:95]
	v_mfma_f32_16x16x32_bf16 v[88:91], v[154:157], v[194:197], v[88:91]
	v_mfma_f32_16x16x32_bf16 v[76:79], v[140:143], v[202:205], v[76:79]
	v_mfma_f32_16x16x32_bf16 v[72:75], v[154:157], v[202:205], v[72:75]
	v_mfma_f32_16x16x32_bf16 v[124:127], v[150:153], v[182:185], v[124:127]
	v_mfma_f32_16x16x32_bf16 v[120:123], v[158:161], v[182:185], v[120:123]
	v_mfma_f32_16x16x32_bf16 v[108:111], v[150:153], v[190:193], v[108:111]
	v_mfma_f32_16x16x32_bf16 v[104:107], v[158:161], v[190:193], v[104:107]
	v_mfma_f32_16x16x32_bf16 v[92:95], v[150:153], v[198:201], v[92:95]
	v_mfma_f32_16x16x32_bf16 v[88:91], v[158:161], v[198:201], v[88:91]
	v_mfma_f32_16x16x32_bf16 v[76:79], v[150:153], v[206:209], v[76:79]
	v_mfma_f32_16x16x32_bf16 v[72:75], v[158:161], v[206:209], v[72:75]
	s_setprio 0
	s_setprio 1
	v_mfma_f32_16x16x32_bf16 v[116:119], v[162:165], v[178:181], v[116:119]
	v_mfma_f32_16x16x32_bf16 v[112:115], v[170:173], v[178:181], v[112:115]
	v_mfma_f32_16x16x32_bf16 v[100:103], v[162:165], v[186:189], v[100:103]
	v_mfma_f32_16x16x32_bf16 v[96:99], v[170:173], v[186:189], v[96:99]
	v_mfma_f32_16x16x32_bf16 v[84:87], v[162:165], v[194:197], v[84:87]
	v_mfma_f32_16x16x32_bf16 v[80:83], v[170:173], v[194:197], v[80:83]
	v_mfma_f32_16x16x32_bf16 v[68:71], v[162:165], v[202:205], v[68:71]
	v_mfma_f32_16x16x32_bf16 v[64:67], v[170:173], v[202:205], v[64:67]
	v_mfma_f32_16x16x32_bf16 v[116:119], v[166:169], v[182:185], v[116:119]
	v_mfma_f32_16x16x32_bf16 v[112:115], v[174:177], v[182:185], v[112:115]
	v_mfma_f32_16x16x32_bf16 v[100:103], v[166:169], v[190:193], v[100:103]
	v_mfma_f32_16x16x32_bf16 v[96:99], v[174:177], v[190:193], v[96:99]
	v_mfma_f32_16x16x32_bf16 v[84:87], v[166:169], v[198:201], v[84:87]
	v_mfma_f32_16x16x32_bf16 v[80:83], v[174:177], v[198:201], v[80:83]
	v_mfma_f32_16x16x32_bf16 v[68:71], v[166:169], v[206:209], v[68:71]
	v_mfma_f32_16x16x32_bf16 v[64:67], v[174:177], v[206:209], v[64:67]
	s_setprio 0
	s_barrier
	s_add_i32 s49, s49, s22
	v_lshl_add_u64 v[144:145], s[16:17], 0, v[134:135]
	s_mov_b32 m0, s49
	ds_read_b128 v[178:181], v149 offset:16384
	ds_read_b128 v[182:185], v149 offset:17408
	ds_read_b128 v[186:189], v149 offset:18432
	ds_read_b128 v[190:193], v149 offset:19456
	ds_read_b128 v[194:197], v149 offset:20480
	ds_read_b128 v[198:201], v149 offset:21504
	ds_read_b128 v[202:205], v149 offset:22528
	ds_read_b128 v[206:209], v149 offset:23552
	global_load_lds_dwordx4 v[144:145], off
	s_add_i32 m0, s49, 0x2000
	s_add_u32 s50, s16, 0x80000
	v_lshl_add_u64 v[144:145], s[16:17], 0, v[130:131]
	s_addc_u32 s51, s17, 0
	s_add_i32 s49, s52, s22
	global_load_lds_dwordx4 v[144:145], off
	v_lshl_add_u64 v[218:219], s[50:51], 0, v[134:135]
	v_lshl_add_u64 v[210:211], s[18:19], 0, v[132:133]
	v_lshl_add_u64 v[220:221], s[50:51], 0, v[130:131]
	v_lshl_add_u64 v[144:145], s[18:19], 0, v[128:129]
	s_waitcnt vmcnt(4)
	s_waitcnt lgkmcnt(0)
	s_barrier
	s_setprio 1
	s_waitcnt lgkmcnt(0)
	s_mov_b32 m0, s49
	v_mfma_f32_16x16x32_bf16 v[60:63], v[140:143], v[178:181], v[60:63]
	v_mfma_f32_16x16x32_bf16 v[56:59], v[154:157], v[178:181], v[56:59]
	v_mfma_f32_16x16x32_bf16 v[44:47], v[140:143], v[186:189], v[44:47]
	v_mfma_f32_16x16x32_bf16 v[40:43], v[154:157], v[186:189], v[40:43]
	global_load_lds_dwordx4 v[218:219], off
	s_add_i32 m0, s49, 0x2000
	v_mfma_f32_16x16x32_bf16 v[28:31], v[140:143], v[194:197], v[28:31]
	v_mfma_f32_16x16x32_bf16 v[24:27], v[154:157], v[194:197], v[24:27]
	v_mfma_f32_16x16x32_bf16 v[12:15], v[140:143], v[202:205], v[12:15]
	v_mfma_f32_16x16x32_bf16 v[8:11], v[154:157], v[202:205], v[8:11]
	v_mfma_f32_16x16x32_bf16 v[60:63], v[150:153], v[182:185], v[60:63]
	v_mfma_f32_16x16x32_bf16 v[56:59], v[158:161], v[182:185], v[56:59]
	v_mfma_f32_16x16x32_bf16 v[44:47], v[150:153], v[190:193], v[44:47]
	v_mfma_f32_16x16x32_bf16 v[40:43], v[158:161], v[190:193], v[40:43]
	global_load_lds_dwordx4 v[220:221], off
	s_mov_b32 m0, s23
	v_mfma_f32_16x16x32_bf16 v[28:31], v[150:153], v[198:201], v[28:31]
	v_mfma_f32_16x16x32_bf16 v[24:27], v[158:161], v[198:201], v[24:27]
	v_mfma_f32_16x16x32_bf16 v[12:15], v[150:153], v[206:209], v[12:15]
	v_mfma_f32_16x16x32_bf16 v[8:11], v[158:161], v[206:209], v[8:11]
	s_setprio 0
	s_setprio 1
	v_mfma_f32_16x16x32_bf16 v[52:55], v[162:165], v[178:181], v[52:55]
	v_mfma_f32_16x16x32_bf16 v[48:51], v[170:173], v[178:181], v[48:51]
	v_mfma_f32_16x16x32_bf16 v[36:39], v[162:165], v[186:189], v[36:39]
	v_mfma_f32_16x16x32_bf16 v[32:35], v[170:173], v[186:189], v[32:35]
	global_load_lds_dwordx4 v[144:145], off
	s_mov_b32 m0, s24
	v_mfma_f32_16x16x32_bf16 v[20:23], v[162:165], v[194:197], v[20:23]
	v_mfma_f32_16x16x32_bf16 v[16:19], v[170:173], v[194:197], v[16:19]
	v_mfma_f32_16x16x32_bf16 v[4:7], v[162:165], v[202:205], v[4:7]
	v_mfma_f32_16x16x32_bf16 v[0:3], v[170:173], v[202:205], v[0:3]
	v_mfma_f32_16x16x32_bf16 v[52:55], v[166:169], v[182:185], v[52:55]
	v_mfma_f32_16x16x32_bf16 v[48:51], v[174:177], v[182:185], v[48:51]
	v_mfma_f32_16x16x32_bf16 v[36:39], v[166:169], v[190:193], v[36:39]
	v_mfma_f32_16x16x32_bf16 v[32:35], v[174:177], v[190:193], v[32:35]
	global_load_lds_dwordx4 v[210:211], off
	v_mfma_f32_16x16x32_bf16 v[20:23], v[166:169], v[198:201], v[20:23]
	v_mfma_f32_16x16x32_bf16 v[16:19], v[174:177], v[198:201], v[16:19]
	v_mfma_f32_16x16x32_bf16 v[4:7], v[166:169], v[206:209], v[4:7]
	v_mfma_f32_16x16x32_bf16 v[0:3], v[174:177], v[206:209], v[0:3]
	s_setprio 0
	s_barrier
	s_add_i32 s49, 0, 0x18000
	s_add_i32 s50, 0, 0x1c000
	v_add_u32_e32 v158, s49, v147
	v_add_u32_e32 v174, s50, v147
	ds_read_b128 v[140:143], v158
	ds_read_b128 v[150:153], v158 offset:1024
	ds_read_b128 v[154:157], v158 offset:2048
	ds_read_b128 v[158:161], v158 offset:3072
	ds_read_b128 v[162:165], v174
	ds_read_b128 v[166:169], v174 offset:1024
	ds_read_b128 v[170:173], v174 offset:2048
	ds_read_b128 v[174:177], v174 offset:3072
	s_add_u32 s18, s18, 0x80000
	s_addc_u32 s19, s19, 0
	s_mov_b32 m0, s25
	v_lshl_add_u64 v[212:213], s[18:19], 0, v[128:129]
	ds_read_b128 v[178:181], v149 offset:32768
	ds_read_b128 v[182:185], v149 offset:33792
	ds_read_b128 v[186:189], v149 offset:34816
	ds_read_b128 v[190:193], v149 offset:35840
	ds_read_b128 v[194:197], v149 offset:36864
	ds_read_b128 v[198:201], v149 offset:37888
	ds_read_b128 v[202:205], v149 offset:38912
	ds_read_b128 v[206:209], v149 offset:39936
	global_load_lds_dwordx4 v[212:213], off
	v_lshl_add_u64 v[212:213], s[18:19], 0, v[132:133]
	s_mov_b32 m0, s26
	s_nop 0
	global_load_lds_dwordx4 v[212:213], off
	s_waitcnt vmcnt(8)
	s_waitcnt lgkmcnt(0)
	s_barrier
	s_setprio 1
	s_waitcnt lgkmcnt(0)
	v_mfma_f32_16x16x32_bf16 v[124:127], v[140:143], v[178:181], v[124:127]
	v_mfma_f32_16x16x32_bf16 v[120:123], v[154:157], v[178:181], v[120:123]
	v_mfma_f32_16x16x32_bf16 v[108:111], v[140:143], v[186:189], v[108:111]
	v_mfma_f32_16x16x32_bf16 v[104:107], v[154:157], v[186:189], v[104:107]
	v_mfma_f32_16x16x32_bf16 v[92:95], v[140:143], v[194:197], v[92:95]
	v_mfma_f32_16x16x32_bf16 v[88:91], v[154:157], v[194:197], v[88:91]
	v_mfma_f32_16x16x32_bf16 v[76:79], v[140:143], v[202:205], v[76:79]
	v_mfma_f32_16x16x32_bf16 v[72:75], v[154:157], v[202:205], v[72:75]
	v_mfma_f32_16x16x32_bf16 v[124:127], v[150:153], v[182:185], v[124:127]
	v_mfma_f32_16x16x32_bf16 v[120:123], v[158:161], v[182:185], v[120:123]
	v_mfma_f32_16x16x32_bf16 v[108:111], v[150:153], v[190:193], v[108:111]
	v_mfma_f32_16x16x32_bf16 v[104:107], v[158:161], v[190:193], v[104:107]
	v_mfma_f32_16x16x32_bf16 v[92:95], v[150:153], v[198:201], v[92:95]
	v_mfma_f32_16x16x32_bf16 v[88:91], v[158:161], v[198:201], v[88:91]
	v_mfma_f32_16x16x32_bf16 v[76:79], v[150:153], v[206:209], v[76:79]
	v_mfma_f32_16x16x32_bf16 v[72:75], v[158:161], v[206:209], v[72:75]
	s_setprio 0
	s_setprio 1
	v_mfma_f32_16x16x32_bf16 v[116:119], v[162:165], v[178:181], v[116:119]
	v_mfma_f32_16x16x32_bf16 v[112:115], v[170:173], v[178:181], v[112:115]
	v_mfma_f32_16x16x32_bf16 v[100:103], v[162:165], v[186:189], v[100:103]
	v_mfma_f32_16x16x32_bf16 v[96:99], v[170:173], v[186:189], v[96:99]
	v_mfma_f32_16x16x32_bf16 v[84:87], v[162:165], v[194:197], v[84:87]
	v_mfma_f32_16x16x32_bf16 v[80:83], v[170:173], v[194:197], v[80:83]
	v_mfma_f32_16x16x32_bf16 v[68:71], v[162:165], v[202:205], v[68:71]
	v_mfma_f32_16x16x32_bf16 v[64:67], v[170:173], v[202:205], v[64:67]
	v_mfma_f32_16x16x32_bf16 v[116:119], v[166:169], v[182:185], v[116:119]
	v_mfma_f32_16x16x32_bf16 v[112:115], v[174:177], v[182:185], v[112:115]
	v_mfma_f32_16x16x32_bf16 v[100:103], v[166:169], v[190:193], v[100:103]
	v_mfma_f32_16x16x32_bf16 v[96:99], v[174:177], v[190:193], v[96:99]
	v_mfma_f32_16x16x32_bf16 v[84:87], v[166:169], v[198:201], v[84:87]
	v_mfma_f32_16x16x32_bf16 v[80:83], v[174:177], v[198:201], v[80:83]
	v_mfma_f32_16x16x32_bf16 v[68:71], v[166:169], v[206:209], v[68:71]
	v_mfma_f32_16x16x32_bf16 v[64:67], v[174:177], v[206:209], v[64:67]
	s_setprio 0
	s_barrier
	s_add_u32 s18, s16, 0x4000
	s_addc_u32 s19, s17, 0
	s_add_i32 s49, s49, s22
	v_lshl_add_u64 v[212:213], s[18:19], 0, v[134:135]
	s_mov_b32 m0, s49
	ds_read_b128 v[178:181], v149 offset:49152
	ds_read_b128 v[182:185], v149 offset:50176
	ds_read_b128 v[186:189], v149 offset:51200
	ds_read_b128 v[190:193], v149 offset:52224
	ds_read_b128 v[194:197], v149 offset:53248
	ds_read_b128 v[198:201], v149 offset:54272
	ds_read_b128 v[202:205], v149 offset:55296
	ds_read_b128 v[206:209], v149 offset:56320
	global_load_lds_dwordx4 v[212:213], off
	s_add_i32 m0, s49, 0x2000
	s_add_u32 s16, s16, 0x84000
	v_lshl_add_u64 v[212:213], s[18:19], 0, v[130:131]
	s_addc_u32 s17, s17, 0
	s_add_i32 s18, s50, s22
	global_load_lds_dwordx4 v[212:213], off
	v_lshl_add_u64 v[218:219], s[16:17], 0, v[134:135]
	v_lshl_add_u64 v[222:223], v[144:145], 0, s[34:35]
	v_lshl_add_u64 v[220:221], s[16:17], 0, v[130:131]
	v_lshl_add_u64 v[144:145], v[210:211], 0, s[34:35]
	s_waitcnt vmcnt(4)
	s_waitcnt lgkmcnt(0)
	s_barrier
	s_setprio 1
	s_waitcnt lgkmcnt(0)
	s_mov_b32 m0, s18
	v_mfma_f32_16x16x32_bf16 v[60:63], v[140:143], v[178:181], v[60:63]
	v_mfma_f32_16x16x32_bf16 v[56:59], v[154:157], v[178:181], v[56:59]
	v_mfma_f32_16x16x32_bf16 v[44:47], v[140:143], v[186:189], v[44:47]
	v_mfma_f32_16x16x32_bf16 v[40:43], v[154:157], v[186:189], v[40:43]
	global_load_lds_dwordx4 v[218:219], off
	s_add_i32 m0, s18, 0x2000
	v_mfma_f32_16x16x32_bf16 v[28:31], v[140:143], v[194:197], v[28:31]
	v_mfma_f32_16x16x32_bf16 v[24:27], v[154:157], v[194:197], v[24:27]
	v_mfma_f32_16x16x32_bf16 v[12:15], v[140:143], v[202:205], v[12:15]
	v_mfma_f32_16x16x32_bf16 v[8:11], v[154:157], v[202:205], v[8:11]
	v_mfma_f32_16x16x32_bf16 v[60:63], v[150:153], v[182:185], v[60:63]
	v_mfma_f32_16x16x32_bf16 v[56:59], v[158:161], v[182:185], v[56:59]
	v_mfma_f32_16x16x32_bf16 v[44:47], v[150:153], v[190:193], v[44:47]
	v_mfma_f32_16x16x32_bf16 v[40:43], v[158:161], v[190:193], v[40:43]
	global_load_lds_dwordx4 v[220:221], off
	s_mov_b32 m0, s28
	v_mfma_f32_16x16x32_bf16 v[28:31], v[150:153], v[198:201], v[28:31]
	v_mfma_f32_16x16x32_bf16 v[24:27], v[158:161], v[198:201], v[24:27]
	v_mfma_f32_16x16x32_bf16 v[12:15], v[150:153], v[206:209], v[12:15]
	v_mfma_f32_16x16x32_bf16 v[8:11], v[158:161], v[206:209], v[8:11]
	s_setprio 0
	s_setprio 1
	v_mfma_f32_16x16x32_bf16 v[52:55], v[162:165], v[178:181], v[52:55]
	v_mfma_f32_16x16x32_bf16 v[48:51], v[170:173], v[178:181], v[48:51]
	v_mfma_f32_16x16x32_bf16 v[36:39], v[162:165], v[186:189], v[36:39]
	v_mfma_f32_16x16x32_bf16 v[32:35], v[170:173], v[186:189], v[32:35]
	global_load_lds_dwordx4 v[222:223], off
	s_mov_b32 m0, s29
	v_mfma_f32_16x16x32_bf16 v[20:23], v[162:165], v[194:197], v[20:23]
	v_mfma_f32_16x16x32_bf16 v[16:19], v[170:173], v[194:197], v[16:19]
	v_mfma_f32_16x16x32_bf16 v[4:7], v[162:165], v[202:205], v[4:7]
	v_mfma_f32_16x16x32_bf16 v[0:3], v[170:173], v[202:205], v[0:3]
	v_mfma_f32_16x16x32_bf16 v[52:55], v[166:169], v[182:185], v[52:55]
	v_mfma_f32_16x16x32_bf16 v[48:51], v[174:177], v[182:185], v[48:51]
	v_mfma_f32_16x16x32_bf16 v[36:39], v[166:169], v[190:193], v[36:39]
	v_mfma_f32_16x16x32_bf16 v[32:35], v[174:177], v[190:193], v[32:35]
	global_load_lds_dwordx4 v[144:145], off
	v_mfma_f32_16x16x32_bf16 v[20:23], v[166:169], v[198:201], v[20:23]
	v_mfma_f32_16x16x32_bf16 v[16:19], v[174:177], v[198:201], v[16:19]
	v_mfma_f32_16x16x32_bf16 v[4:7], v[166:169], v[206:209], v[4:7]
	v_mfma_f32_16x16x32_bf16 v[0:3], v[174:177], v[206:209], v[0:3]
	s_setprio 0
	s_barrier
	s_add_i32 s48, s48, 2
	s_add_u32 s46, s46, 0x8000
	s_addc_u32 s47, s47, 0
	s_add_u32 s14, s14, 0x100
	s_addc_u32 s15, s15, 0
	s_cmp_gt_u32 s48, 29
	s_cbranch_scc0 .LBB0_101
	s_and_b64 vcc, exec, s[6:7]
	s_cbranch_vccz .LBB0_104
	s_barrier
